# hand-written mode-6 compaction sweep: pk clamp relu, pipelined LDS atomics, branch-free
# speedup vs baseline: 1.0554x; 1.0356x over previous
;     ...
;     const int kt0 = wid >> 1; const int nit = kt0 <= c ? 2 * ((c - kt0) / 4 + 1) : 0;
;     const float t_lo = bucket_lo((int)pref), t_hi = bucket_lo((int)pref + 1);
;     const bf16_t* ikp = Zb + (size_t)(64 * kt0 + r32) * NZ + ZIK + hi * 8;
;     bf16x8 a0, a1;
;     if (nit > 0) { a0 = *(const bf16x8*)ikp; a1 = *(const bf16x8*)(ikp + 16); }
; #pragma unroll 1
;     for (int it = 0; it < nit; ++it) {
;         const int kt = kt0 + 4 * (it >> 1), kb = it & 1;
;         const int itn = it + 1 < nit ? it + 1 : it;
;         const bf16_t* np = ikp + (size_t)(256 * (itn >> 1) + 32 * (itn & 1)) * NZ; const bf16x8 n0 = *(const bf16x8*)np, n1 = *(const bf16x8*)(np + 16);
;         f32x2v sc2[8];
; #pragma unroll
;         for (int r = 0; r < 8; ++r) sc2[r] = (f32x2v){0.f, 0.f};
;     ...
;         { f32x16 zero16;
; #pragma unroll
;           for (int r = 0; r < 16; ++r) zero16[r] = 0.f;
;           f32x16 dA0, dA1, dB0, dB1; float wA0, wA1, wB0, wB1;
;           SW_MF(0, dA0, dA1, wA0, wA1);
;           SW_MF(1, dB0, dB1, wB0, wB1); __builtin_amdgcn_sched_barrier(0);
;           SW_VA(dA0, dA1, wA0, wA1);    __builtin_amdgcn_sched_barrier(0);
;           SW_MF(2, dA0, dA1, wA0, wA1); __builtin_amdgcn_sched_barrier(0);
;           SW_VA(dB0, dB1, wB0, wB1);    __builtin_amdgcn_sched_barrier(0);
;           SW_MF(3, dB0, dB1, wB0, wB1); __builtin_amdgcn_sched_barrier(0);
;           SW_VA(dA0, dA1, wA0, wA1);    __builtin_amdgcn_sched_barrier(0);
;           SW_VA(dB0, dB1, wB0, wB1); }
;     ...
;         f32x16 sc;
; #pragma unroll
;         for (int r = 0; r < 16; ++r) sc[r] = sc2[r >> 1][r & 1];
;         const unsigned s0 = (unsigned)(64 * kt + 32 * kb + 4 * hi);
; #pragma unroll
;         for (int r = 0; r < 16; ++r) { const unsigned s = s0 + (unsigned)((r & 3) + 8 * (r >> 2));
;             if (MODE == 5) { __hip_atomic_fetch_add(hist + 64 * bucketf(sc[r]), 1u, __ATOMIC_RELAXED, __HIP_MEMORY_SCOPE_WORKGROUP); continue; }
;             if (MODE == 6) {
;                 if (sc[r] >= t_hi) { const unsigned pos = __hip_atomic_fetch_add(cnt, 1u, __ATOMIC_RELAXED, __HIP_MEMORY_SCOPE_WORKGROUP); sel[pos & 255u] = (unsigned short)s; }
;                 else if (sc[r] >= t_lo) { const unsigned key = (sortable(sc[r]) & 0xFFFFE000u) | (8191u - s);
.LBB0_1521:
	s_and_b64 vcc, exec, s[18:19]
	s_cbranch_vccnz .LBB0_1620
	v_lshl_add_u32 v179, v169, 9, s57
	v_add_u32_e32 v180, s94, v171
	v_lshl_add_u32 v169, v169, 10, v200
	v_add_u32_e32 v171, s33, v171
	v_mov_b32_e32 v112, 0x2c800000
	v_mov_b32_e32 v113, 0x2c800000
	v_mul_f32_e32 v122, 0x2c800000, v154
	v_mul_f32_e32 v123, 0x2c800000, v178
	s_mov_b32 s18, 0
.Lm6_loop:
	s_add_i32 s1, s18, 1
	s_cmp_lt_u32 s1, s25
	s_cselect_b32 s3, s1, s18
	s_lshl_b32 vcc_lo, s3, 7
	s_and_b32 vcc_lo, vcc_lo, 0x7fffff00
	s_lshl_b32 s3, s3, 5
	s_and_b32 s3, s3, 32
	s_or_b32 s3, vcc_lo, s3
	s_lshr_b32 s0, s18, 1
	s_lshl_b32 s0, s0, 2
	s_add_i32 s0, s0, s24
	s_lshl_b32 s0, s0, 6
	s_and_b32 s2, s18, 1
	s_lshl_b32 s2, s2, 5
	s_or_b32 s0, s0, s2
	ds_read_b128 v[0:3], v165
	ds_read_b128 v[4:7], v165 offset:32
	ds_read_b128 v[8:11], v165 offset:64
	ds_read_b128 v[12:15], v165 offset:96
	ds_read2st64_b32 v[80:81], v167 offset1:1
	ds_read2st64_b32 v[82:83], v167 offset0:2 offset1:3
	ds_read2st64_b32 v[84:85], v167 offset0:4 offset1:5
	ds_read2st64_b32 v[86:87], v167 offset0:6 offset1:7
	v_mad_u64_u32 v[114:115], vcc, s3, v223, v[140:141]
	v_or_b32_e32 v124, s0, v159
	global_load_dwordx4 v[64:67], v[114:115], off
	global_load_dwordx4 v[68:71], v[114:115], off offset:32
	s_waitcnt vmcnt(2) lgkmcnt(6)
	v_mfma_f32_32x32x16_bf16 v[16:31], v[132:135], v[0:3], 0
	v_mfma_f32_32x32x16_bf16 v[16:31], v[128:131], v[4:7], v[16:31]
	ds_read_b128 v[0:3], v165 offset:128
	ds_read_b128 v[4:7], v165 offset:160
	s_waitcnt lgkmcnt(6)
	v_mfma_f32_32x32x16_bf16 v[32:47], v[132:135], v[8:11], 0
	v_mfma_f32_32x32x16_bf16 v[32:47], v[128:131], v[12:15], v[32:47]
	ds_read_b128 v[8:11], v165 offset:192
	ds_read_b128 v[12:15], v165 offset:224
	s_nop 7
	s_waitcnt lgkmcnt(4)
	v_mov_b32_e32 v104, v81
	v_mov_b32_e32 v106, v83
	v_mov_b32_e32 v108, v85
	v_mov_b32_e32 v110, v87
	v_pk_mul_f32 v[16:17], v[16:17], v[112:113] clamp
	v_pk_mul_f32 v[18:19], v[18:19], v[112:113] clamp
	v_pk_mul_f32 v[20:21], v[20:21], v[112:113] clamp
	v_pk_mul_f32 v[22:23], v[22:23], v[112:113] clamp
	v_pk_mul_f32 v[24:25], v[24:25], v[112:113] clamp
	v_pk_mul_f32 v[26:27], v[26:27], v[112:113] clamp
	v_pk_mul_f32 v[28:29], v[28:29], v[112:113] clamp
	v_pk_mul_f32 v[30:31], v[30:31], v[112:113] clamp
	v_pk_fma_f32 v[88:89], v[16:17], v[80:81], 0 op_sel_hi:[1,0,0]
	v_pk_fma_f32 v[90:91], v[18:19], v[80:81], 0 op_sel_hi:[1,0,0]
	v_pk_fma_f32 v[92:93], v[20:21], v[80:81], 0 op_sel_hi:[1,0,0]
	v_pk_fma_f32 v[94:95], v[22:23], v[80:81], 0 op_sel_hi:[1,0,0]
	v_pk_fma_f32 v[96:97], v[24:25], v[80:81], 0 op_sel_hi:[1,0,0]
	v_pk_fma_f32 v[98:99], v[26:27], v[80:81], 0 op_sel_hi:[1,0,0]
	v_pk_fma_f32 v[100:101], v[28:29], v[80:81], 0 op_sel_hi:[1,0,0]
	v_pk_fma_f32 v[102:103], v[30:31], v[80:81], 0 op_sel_hi:[1,0,0]
	s_waitcnt lgkmcnt(2)
	v_mfma_f32_32x32x16_bf16 v[16:31], v[132:135], v[0:3], 0
	v_mfma_f32_32x32x16_bf16 v[16:31], v[128:131], v[4:7], v[16:31]
	ds_read_b128 v[0:3], v165 offset:256
	ds_read_b128 v[4:7], v165 offset:288
	v_pk_mul_f32 v[32:33], v[32:33], v[112:113] clamp
	v_pk_mul_f32 v[34:35], v[34:35], v[112:113] clamp
	v_pk_mul_f32 v[36:37], v[36:37], v[112:113] clamp
	v_pk_mul_f32 v[38:39], v[38:39], v[112:113] clamp
	v_pk_mul_f32 v[40:41], v[40:41], v[112:113] clamp
	v_pk_mul_f32 v[42:43], v[42:43], v[112:113] clamp
	v_pk_mul_f32 v[44:45], v[44:45], v[112:113] clamp
	v_pk_mul_f32 v[46:47], v[46:47], v[112:113] clamp
	v_pk_fma_f32 v[88:89], v[32:33], v[104:105], v[88:89] op_sel_hi:[1,0,1]
	v_pk_fma_f32 v[90:91], v[34:35], v[104:105], v[90:91] op_sel_hi:[1,0,1]
	v_pk_fma_f32 v[92:93], v[36:37], v[104:105], v[92:93] op_sel_hi:[1,0,1]
	v_pk_fma_f32 v[94:95], v[38:39], v[104:105], v[94:95] op_sel_hi:[1,0,1]
	v_pk_fma_f32 v[96:97], v[40:41], v[104:105], v[96:97] op_sel_hi:[1,0,1]
	v_pk_fma_f32 v[98:99], v[42:43], v[104:105], v[98:99] op_sel_hi:[1,0,1]
	v_pk_fma_f32 v[100:101], v[44:45], v[104:105], v[100:101] op_sel_hi:[1,0,1]
	v_pk_fma_f32 v[102:103], v[46:47], v[104:105], v[102:103] op_sel_hi:[1,0,1]
	s_waitcnt lgkmcnt(2)
	v_mfma_f32_32x32x16_bf16 v[32:47], v[132:135], v[8:11], 0
	v_mfma_f32_32x32x16_bf16 v[32:47], v[128:131], v[12:15], v[32:47]
	ds_read_b128 v[8:11], v165 offset:320
	ds_read_b128 v[12:15], v165 offset:352
	v_pk_mul_f32 v[16:17], v[16:17], v[112:113] clamp
	v_pk_mul_f32 v[18:19], v[18:19], v[112:113] clamp
	v_pk_mul_f32 v[20:21], v[20:21], v[112:113] clamp
	v_pk_mul_f32 v[22:23], v[22:23], v[112:113] clamp
	v_pk_mul_f32 v[24:25], v[24:25], v[112:113] clamp
	v_pk_mul_f32 v[26:27], v[26:27], v[112:113] clamp
	v_pk_mul_f32 v[28:29], v[28:29], v[112:113] clamp
	v_pk_mul_f32 v[30:31], v[30:31], v[112:113] clamp
	v_pk_fma_f32 v[88:89], v[16:17], v[82:83], v[88:89] op_sel_hi:[1,0,1]
	v_pk_fma_f32 v[90:91], v[18:19], v[82:83], v[90:91] op_sel_hi:[1,0,1]
	v_pk_fma_f32 v[92:93], v[20:21], v[82:83], v[92:93] op_sel_hi:[1,0,1]
	v_pk_fma_f32 v[94:95], v[22:23], v[82:83], v[94:95] op_sel_hi:[1,0,1]
	v_pk_fma_f32 v[96:97], v[24:25], v[82:83], v[96:97] op_sel_hi:[1,0,1]
	v_pk_fma_f32 v[98:99], v[26:27], v[82:83], v[98:99] op_sel_hi:[1,0,1]
	v_pk_fma_f32 v[100:101], v[28:29], v[82:83], v[100:101] op_sel_hi:[1,0,1]
	v_pk_fma_f32 v[102:103], v[30:31], v[82:83], v[102:103] op_sel_hi:[1,0,1]
	s_waitcnt lgkmcnt(2)
; __device__ __forceinline__ unsigned sortable(float f) { const unsigned u = __float_as_uint(f); return u ^ ((unsigned)((int)u >> 31) | 0x80000000u); }
; __device__ __forceinline__ int bucketf(float f) { const unsigned u = __float_as_uint(f); const int idx = (int)((u >> 20) & 0x7FFu); const int c = min(max(idx - 816, 128), 255); return c ^ (((int)u >> 31) & 255); }
;     ...
;         { f32x16 zero16;
; #pragma unroll
;           for (int r = 0; r < 16; ++r) zero16[r] = 0.f;
;           f32x16 dA0, dA1, dB0, dB1; float wA0, wA1, wB0, wB1;
;           SW_MF(0, dA0, dA1, wA0, wA1);
;           SW_MF(1, dB0, dB1, wB0, wB1); __builtin_amdgcn_sched_barrier(0);
;           SW_VA(dA0, dA1, wA0, wA1);    __builtin_amdgcn_sched_barrier(0);
;           SW_MF(2, dA0, dA1, wA0, wA1); __builtin_amdgcn_sched_barrier(0);
;           SW_VA(dB0, dB1, wB0, wB1);    __builtin_amdgcn_sched_barrier(0);
;           SW_MF(3, dB0, dB1, wB0, wB1); __builtin_amdgcn_sched_barrier(0);
;           SW_VA(dA0, dA1, wA0, wA1);    __builtin_amdgcn_sched_barrier(0);
;           SW_VA(dB0, dB1, wB0, wB1); }
;     ...
;         f32x16 sc;
; #pragma unroll
;         for (int r = 0; r < 16; ++r) sc[r] = sc2[r >> 1][r & 1];
;         const unsigned s0 = (unsigned)(64 * kt + 32 * kb + 4 * hi);
; #pragma unroll
;         for (int r = 0; r < 16; ++r) { const unsigned s = s0 + (unsigned)((r & 3) + 8 * (r >> 2));
;             if (MODE == 5) { __hip_atomic_fetch_add(hist + 64 * bucketf(sc[r]), 1u, __ATOMIC_RELAXED, __HIP_MEMORY_SCOPE_WORKGROUP); continue; }
;             if (MODE == 6) {
;                 if (sc[r] >= t_hi) { const unsigned pos = __hip_atomic_fetch_add(cnt, 1u, __ATOMIC_RELAXED, __HIP_MEMORY_SCOPE_WORKGROUP); sel[pos & 255u] = (unsigned short)s; }
;                 else if (sc[r] >= t_lo) { const unsigned key = (sortable(sc[r]) & 0xFFFFE000u) | (8191u - s);
;                     const unsigned pos = __hip_atomic_fetch_add(ccnt, 1u, __ATOMIC_RELAXED, __HIP_MEMORY_SCOPE_WORKGROUP); cand[pos & (DS_CAP - 1)] = key; }
;                 continue; }
	v_mfma_f32_32x32x16_bf16 v[16:31], v[132:135], v[0:3], 0
	v_mfma_f32_32x32x16_bf16 v[16:31], v[128:131], v[4:7], v[16:31]
	ds_read_b128 v[0:3], v165 offset:384
	ds_read_b128 v[4:7], v165 offset:416
	v_pk_mul_f32 v[32:33], v[32:33], v[112:113] clamp
	v_pk_mul_f32 v[34:35], v[34:35], v[112:113] clamp
	v_pk_mul_f32 v[36:37], v[36:37], v[112:113] clamp
	v_pk_mul_f32 v[38:39], v[38:39], v[112:113] clamp
	v_pk_mul_f32 v[40:41], v[40:41], v[112:113] clamp
	v_pk_mul_f32 v[42:43], v[42:43], v[112:113] clamp
	v_pk_mul_f32 v[44:45], v[44:45], v[112:113] clamp
	v_pk_mul_f32 v[46:47], v[46:47], v[112:113] clamp
	v_pk_fma_f32 v[88:89], v[32:33], v[106:107], v[88:89] op_sel_hi:[1,0,1]
	v_pk_fma_f32 v[90:91], v[34:35], v[106:107], v[90:91] op_sel_hi:[1,0,1]
	v_pk_fma_f32 v[92:93], v[36:37], v[106:107], v[92:93] op_sel_hi:[1,0,1]
	v_pk_fma_f32 v[94:95], v[38:39], v[106:107], v[94:95] op_sel_hi:[1,0,1]
	v_pk_fma_f32 v[96:97], v[40:41], v[106:107], v[96:97] op_sel_hi:[1,0,1]
	v_pk_fma_f32 v[98:99], v[42:43], v[106:107], v[98:99] op_sel_hi:[1,0,1]
	v_pk_fma_f32 v[100:101], v[44:45], v[106:107], v[100:101] op_sel_hi:[1,0,1]
	v_pk_fma_f32 v[102:103], v[46:47], v[106:107], v[102:103] op_sel_hi:[1,0,1]
	s_waitcnt lgkmcnt(2)
	v_mfma_f32_32x32x16_bf16 v[32:47], v[132:135], v[8:11], 0
	v_mfma_f32_32x32x16_bf16 v[32:47], v[128:131], v[12:15], v[32:47]
	ds_read_b128 v[8:11], v165 offset:448
	ds_read_b128 v[12:15], v165 offset:480
	v_pk_mul_f32 v[16:17], v[16:17], v[112:113] clamp
	v_pk_mul_f32 v[18:19], v[18:19], v[112:113] clamp
	v_pk_mul_f32 v[20:21], v[20:21], v[112:113] clamp
	v_pk_mul_f32 v[22:23], v[22:23], v[112:113] clamp
	v_pk_mul_f32 v[24:25], v[24:25], v[112:113] clamp
	v_pk_mul_f32 v[26:27], v[26:27], v[112:113] clamp
	v_pk_mul_f32 v[28:29], v[28:29], v[112:113] clamp
	v_pk_mul_f32 v[30:31], v[30:31], v[112:113] clamp
	v_pk_fma_f32 v[88:89], v[16:17], v[84:85], v[88:89] op_sel_hi:[1,0,1]
	v_pk_fma_f32 v[90:91], v[18:19], v[84:85], v[90:91] op_sel_hi:[1,0,1]
	v_pk_fma_f32 v[92:93], v[20:21], v[84:85], v[92:93] op_sel_hi:[1,0,1]
	v_pk_fma_f32 v[94:95], v[22:23], v[84:85], v[94:95] op_sel_hi:[1,0,1]
	v_pk_fma_f32 v[96:97], v[24:25], v[84:85], v[96:97] op_sel_hi:[1,0,1]
	v_pk_fma_f32 v[98:99], v[26:27], v[84:85], v[98:99] op_sel_hi:[1,0,1]
	v_pk_fma_f32 v[100:101], v[28:29], v[84:85], v[100:101] op_sel_hi:[1,0,1]
	v_pk_fma_f32 v[102:103], v[30:31], v[84:85], v[102:103] op_sel_hi:[1,0,1]
	s_waitcnt lgkmcnt(2)
	v_mfma_f32_32x32x16_bf16 v[16:31], v[132:135], v[0:3], 0
	v_mfma_f32_32x32x16_bf16 v[16:31], v[128:131], v[4:7], v[16:31]
	v_pk_mul_f32 v[32:33], v[32:33], v[112:113] clamp
	v_pk_mul_f32 v[34:35], v[34:35], v[112:113] clamp
	v_pk_mul_f32 v[36:37], v[36:37], v[112:113] clamp
	v_pk_mul_f32 v[38:39], v[38:39], v[112:113] clamp
	v_pk_mul_f32 v[40:41], v[40:41], v[112:113] clamp
	v_pk_mul_f32 v[42:43], v[42:43], v[112:113] clamp
	v_pk_mul_f32 v[44:45], v[44:45], v[112:113] clamp
	v_pk_mul_f32 v[46:47], v[46:47], v[112:113] clamp
	v_pk_fma_f32 v[88:89], v[32:33], v[108:109], v[88:89] op_sel_hi:[1,0,1]
	v_pk_fma_f32 v[90:91], v[34:35], v[108:109], v[90:91] op_sel_hi:[1,0,1]
	v_pk_fma_f32 v[92:93], v[36:37], v[108:109], v[92:93] op_sel_hi:[1,0,1]
	v_pk_fma_f32 v[94:95], v[38:39], v[108:109], v[94:95] op_sel_hi:[1,0,1]
	v_pk_fma_f32 v[96:97], v[40:41], v[108:109], v[96:97] op_sel_hi:[1,0,1]
	v_pk_fma_f32 v[98:99], v[42:43], v[108:109], v[98:99] op_sel_hi:[1,0,1]
	v_pk_fma_f32 v[100:101], v[44:45], v[108:109], v[100:101] op_sel_hi:[1,0,1]
	v_pk_fma_f32 v[102:103], v[46:47], v[108:109], v[102:103] op_sel_hi:[1,0,1]
	s_waitcnt lgkmcnt(0)
	v_mfma_f32_32x32x16_bf16 v[32:47], v[132:135], v[8:11], 0
	v_mfma_f32_32x32x16_bf16 v[32:47], v[128:131], v[12:15], v[32:47]
	v_pk_mul_f32 v[16:17], v[16:17], v[112:113] clamp
	v_pk_mul_f32 v[18:19], v[18:19], v[112:113] clamp
	v_pk_mul_f32 v[20:21], v[20:21], v[112:113] clamp
	v_pk_mul_f32 v[22:23], v[22:23], v[112:113] clamp
	v_pk_mul_f32 v[24:25], v[24:25], v[112:113] clamp
	v_pk_mul_f32 v[26:27], v[26:27], v[112:113] clamp
	v_pk_mul_f32 v[28:29], v[28:29], v[112:113] clamp
	v_pk_mul_f32 v[30:31], v[30:31], v[112:113] clamp
	v_pk_fma_f32 v[88:89], v[16:17], v[86:87], v[88:89] op_sel_hi:[1,0,1]
	v_pk_fma_f32 v[90:91], v[18:19], v[86:87], v[90:91] op_sel_hi:[1,0,1]
	v_pk_fma_f32 v[92:93], v[20:21], v[86:87], v[92:93] op_sel_hi:[1,0,1]
	v_pk_fma_f32 v[94:95], v[22:23], v[86:87], v[94:95] op_sel_hi:[1,0,1]
	v_pk_fma_f32 v[96:97], v[24:25], v[86:87], v[96:97] op_sel_hi:[1,0,1]
	v_pk_fma_f32 v[98:99], v[26:27], v[86:87], v[98:99] op_sel_hi:[1,0,1]
	v_pk_fma_f32 v[100:101], v[28:29], v[86:87], v[100:101] op_sel_hi:[1,0,1]
	v_pk_fma_f32 v[102:103], v[30:31], v[86:87], v[102:103] op_sel_hi:[1,0,1]
	v_pk_mul_f32 v[32:33], v[32:33], v[112:113] clamp
	v_pk_mul_f32 v[34:35], v[34:35], v[112:113] clamp
	v_pk_mul_f32 v[36:37], v[36:37], v[112:113] clamp
	v_pk_mul_f32 v[38:39], v[38:39], v[112:113] clamp
	v_pk_mul_f32 v[40:41], v[40:41], v[112:113] clamp
	v_pk_mul_f32 v[42:43], v[42:43], v[112:113] clamp
	v_pk_mul_f32 v[44:45], v[44:45], v[112:113] clamp
	v_pk_mul_f32 v[46:47], v[46:47], v[112:113] clamp
	v_pk_fma_f32 v[88:89], v[32:33], v[110:111], v[88:89] op_sel_hi:[1,0,1]
	v_pk_fma_f32 v[90:91], v[34:35], v[110:111], v[90:91] op_sel_hi:[1,0,1]
	v_pk_fma_f32 v[92:93], v[36:37], v[110:111], v[92:93] op_sel_hi:[1,0,1]
	v_pk_fma_f32 v[94:95], v[38:39], v[110:111], v[94:95] op_sel_hi:[1,0,1]
	v_pk_fma_f32 v[96:97], v[40:41], v[110:111], v[96:97] op_sel_hi:[1,0,1]
	v_pk_fma_f32 v[98:99], v[42:43], v[110:111], v[98:99] op_sel_hi:[1,0,1]
	v_pk_fma_f32 v[100:101], v[44:45], v[110:111], v[100:101] op_sel_hi:[1,0,1]
	v_pk_fma_f32 v[102:103], v[46:47], v[110:111], v[102:103] op_sel_hi:[1,0,1]
	v_cmp_ge_f32_e64 s[40:41], v88, v122
	v_cmp_ge_f32_e64 s[42:43], v88, v123
	s_andn2_b64 s[42:43], s[42:43], s[40:41]
	s_mov_b64 exec, s[40:41]
	ds_add_rtn_u32 v16, v180, v222
	s_mov_b64 exec, s[42:43]
	ds_add_rtn_u32 v16, v171, v222
	s_mov_b64 exec, -1
	v_cmp_ge_f32_e64 s[44:45], v89, v122
	v_cmp_ge_f32_e64 s[22:23], v89, v123
	s_andn2_b64 s[22:23], s[22:23], s[44:45]
	s_mov_b64 exec, s[44:45]
	ds_add_rtn_u32 v17, v180, v222
	s_mov_b64 exec, s[22:23]
	ds_add_rtn_u32 v17, v171, v222
	s_mov_b64 exec, -1
	v_mov_b32_e32 v18, v124
	s_waitcnt lgkmcnt(2)
; __device__ __forceinline__ unsigned sortable(float f) { const unsigned u = __float_as_uint(f); return u ^ ((unsigned)((int)u >> 31) | 0x80000000u); }
; __device__ __forceinline__ int bucketf(float f) { const unsigned u = __float_as_uint(f); const int idx = (int)((u >> 20) & 0x7FFu); const int c = min(max(idx - 816, 128), 255); return c ^ (((int)u >> 31) & 255); }
;     ...
;         const unsigned s0 = (unsigned)(64 * kt + 32 * kb + 4 * hi);
; #pragma unroll
;         for (int r = 0; r < 16; ++r) { const unsigned s = s0 + (unsigned)((r & 3) + 8 * (r >> 2));
;             if (MODE == 5) { __hip_atomic_fetch_add(hist + 64 * bucketf(sc[r]), 1u, __ATOMIC_RELAXED, __HIP_MEMORY_SCOPE_WORKGROUP); continue; }
;             if (MODE == 6) {
;                 if (sc[r] >= t_hi) { const unsigned pos = __hip_atomic_fetch_add(cnt, 1u, __ATOMIC_RELAXED, __HIP_MEMORY_SCOPE_WORKGROUP); sel[pos & 255u] = (unsigned short)s; }
;                 else if (sc[r] >= t_lo) { const unsigned key = (sortable(sc[r]) & 0xFFFFE000u) | (8191u - s);
;                     const unsigned pos = __hip_atomic_fetch_add(ccnt, 1u, __ATOMIC_RELAXED, __HIP_MEMORY_SCOPE_WORKGROUP); cand[pos & (DS_CAP - 1)] = key; }
;                 continue; }
	v_and_b32_e32 v16, 0xff, v16
	s_mov_b64 exec, s[40:41]
	v_lshl_add_u32 v20, v16, 1, v179
	ds_write_b16 v20, v18
	s_mov_b64 exec, s[42:43]
	v_mul_f32_e32 v21, 0x52800000, v88
	v_sub_u32_e32 v18, 0x1fff, v18
	v_ashrrev_i32_e32 v22, 31, v21
	v_lshl_add_u32 v20, v16, 2, v169
	v_bitop3_b32 v21, v22, v21, s64 bitop3:0x36
	v_and_or_b32 v21, v21, s65, v18
	ds_write_b32 v20, v21
	s_mov_b64 exec, -1
	v_cmp_ge_f32_e64 s[40:41], v90, v122
	v_cmp_ge_f32_e64 s[42:43], v90, v123
	s_andn2_b64 s[42:43], s[42:43], s[40:41]
	s_mov_b64 exec, s[40:41]
	ds_add_rtn_u32 v16, v180, v222
	s_mov_b64 exec, s[42:43]
	ds_add_rtn_u32 v16, v171, v222
	s_mov_b64 exec, -1
	v_or_b32_e32 v19, 1, v124
	s_waitcnt lgkmcnt(4)
	v_and_b32_e32 v17, 0xff, v17
	s_mov_b64 exec, s[44:45]
	v_lshl_add_u32 v20, v17, 1, v179
	ds_write_b16 v20, v19
	s_mov_b64 exec, s[22:23]
	v_mul_f32_e32 v21, 0x52800000, v89
	v_sub_u32_e32 v19, 0x1fff, v19
	v_ashrrev_i32_e32 v22, 31, v21
	v_lshl_add_u32 v20, v17, 2, v169
	v_bitop3_b32 v21, v22, v21, s64 bitop3:0x36
	v_and_or_b32 v21, v21, s65, v19
	ds_write_b32 v20, v21
	s_mov_b64 exec, -1
	v_cmp_ge_f32_e64 s[44:45], v91, v122
	v_cmp_ge_f32_e64 s[22:23], v91, v123
	s_andn2_b64 s[22:23], s[22:23], s[44:45]
	s_mov_b64 exec, s[44:45]
	ds_add_rtn_u32 v17, v180, v222
	s_mov_b64 exec, s[22:23]
	ds_add_rtn_u32 v17, v171, v222
	s_mov_b64 exec, -1
	v_or_b32_e32 v18, 2, v124
	s_waitcnt lgkmcnt(4)
	v_and_b32_e32 v16, 0xff, v16
	s_mov_b64 exec, s[40:41]
	v_lshl_add_u32 v20, v16, 1, v179
	ds_write_b16 v20, v18
	s_mov_b64 exec, s[42:43]
	v_mul_f32_e32 v21, 0x52800000, v90
	v_sub_u32_e32 v18, 0x1fff, v18
	v_ashrrev_i32_e32 v22, 31, v21
	v_lshl_add_u32 v20, v16, 2, v169
	v_bitop3_b32 v21, v22, v21, s64 bitop3:0x36
	v_and_or_b32 v21, v21, s65, v18
	ds_write_b32 v20, v21
	s_mov_b64 exec, -1
	v_cmp_ge_f32_e64 s[40:41], v92, v122
	v_cmp_ge_f32_e64 s[42:43], v92, v123
	s_andn2_b64 s[42:43], s[42:43], s[40:41]
	s_mov_b64 exec, s[40:41]
	ds_add_rtn_u32 v16, v180, v222
	s_mov_b64 exec, s[42:43]
	ds_add_rtn_u32 v16, v171, v222
	s_mov_b64 exec, -1
	v_or_b32_e32 v19, 3, v124
	s_waitcnt lgkmcnt(4)
	v_and_b32_e32 v17, 0xff, v17
	s_mov_b64 exec, s[44:45]
	v_lshl_add_u32 v20, v17, 1, v179
	ds_write_b16 v20, v19
	s_mov_b64 exec, s[22:23]
	v_mul_f32_e32 v21, 0x52800000, v91
	v_sub_u32_e32 v19, 0x1fff, v19
	v_ashrrev_i32_e32 v22, 31, v21
	v_lshl_add_u32 v20, v17, 2, v169
	v_bitop3_b32 v21, v22, v21, s64 bitop3:0x36
	v_and_or_b32 v21, v21, s65, v19
	ds_write_b32 v20, v21
	s_mov_b64 exec, -1
	v_cmp_ge_f32_e64 s[44:45], v93, v122
	v_cmp_ge_f32_e64 s[22:23], v93, v123
	s_andn2_b64 s[22:23], s[22:23], s[44:45]
	s_mov_b64 exec, s[44:45]
	ds_add_rtn_u32 v17, v180, v222
	s_mov_b64 exec, s[22:23]
	ds_add_rtn_u32 v17, v171, v222
	s_mov_b64 exec, -1
	v_or_b32_e32 v18, 8, v124
	s_waitcnt lgkmcnt(4)
	v_and_b32_e32 v16, 0xff, v16
	s_mov_b64 exec, s[40:41]
	v_lshl_add_u32 v20, v16, 1, v179
	ds_write_b16 v20, v18
	s_mov_b64 exec, s[42:43]
	v_mul_f32_e32 v21, 0x52800000, v92
	v_sub_u32_e32 v18, 0x1fff, v18
	v_ashrrev_i32_e32 v22, 31, v21
	v_lshl_add_u32 v20, v16, 2, v169
	v_bitop3_b32 v21, v22, v21, s64 bitop3:0x36
	v_and_or_b32 v21, v21, s65, v18
	ds_write_b32 v20, v21
	s_mov_b64 exec, -1
	v_cmp_ge_f32_e64 s[40:41], v94, v122
	v_cmp_ge_f32_e64 s[42:43], v94, v123
	s_andn2_b64 s[42:43], s[42:43], s[40:41]
	s_mov_b64 exec, s[40:41]
	ds_add_rtn_u32 v16, v180, v222
	s_mov_b64 exec, s[42:43]
	ds_add_rtn_u32 v16, v171, v222
	s_mov_b64 exec, -1
	v_or_b32_e32 v19, 9, v124
	s_waitcnt lgkmcnt(4)
	v_and_b32_e32 v17, 0xff, v17
	s_mov_b64 exec, s[44:45]
	v_lshl_add_u32 v20, v17, 1, v179
	ds_write_b16 v20, v19
	s_mov_b64 exec, s[22:23]
	v_mul_f32_e32 v21, 0x52800000, v93
	v_sub_u32_e32 v19, 0x1fff, v19
	v_ashrrev_i32_e32 v22, 31, v21
	v_lshl_add_u32 v20, v17, 2, v169
	v_bitop3_b32 v21, v22, v21, s64 bitop3:0x36
	v_and_or_b32 v21, v21, s65, v19
	ds_write_b32 v20, v21
	s_mov_b64 exec, -1
	v_cmp_ge_f32_e64 s[44:45], v95, v122
	v_cmp_ge_f32_e64 s[22:23], v95, v123
	s_andn2_b64 s[22:23], s[22:23], s[44:45]
	s_mov_b64 exec, s[44:45]
	ds_add_rtn_u32 v17, v180, v222
	s_mov_b64 exec, s[22:23]
	ds_add_rtn_u32 v17, v171, v222
	s_mov_b64 exec, -1
	v_or_b32_e32 v18, 10, v124
	s_waitcnt lgkmcnt(4)
	v_and_b32_e32 v16, 0xff, v16
	s_mov_b64 exec, s[40:41]
	v_lshl_add_u32 v20, v16, 1, v179
	ds_write_b16 v20, v18
	s_mov_b64 exec, s[42:43]
	v_mul_f32_e32 v21, 0x52800000, v94
	v_sub_u32_e32 v18, 0x1fff, v18
	v_ashrrev_i32_e32 v22, 31, v21
	v_lshl_add_u32 v20, v16, 2, v169
	v_bitop3_b32 v21, v22, v21, s64 bitop3:0x36
	v_and_or_b32 v21, v21, s65, v18
	ds_write_b32 v20, v21
	s_mov_b64 exec, -1
	v_cmp_ge_f32_e64 s[40:41], v96, v122
	v_cmp_ge_f32_e64 s[42:43], v96, v123
	s_andn2_b64 s[42:43], s[42:43], s[40:41]
	s_mov_b64 exec, s[40:41]
	ds_add_rtn_u32 v16, v180, v222
	s_mov_b64 exec, s[42:43]
	ds_add_rtn_u32 v16, v171, v222
	s_mov_b64 exec, -1
	v_or_b32_e32 v19, 11, v124
	s_waitcnt lgkmcnt(4)
	v_and_b32_e32 v17, 0xff, v17
	s_mov_b64 exec, s[44:45]
	v_lshl_add_u32 v20, v17, 1, v179
	ds_write_b16 v20, v19
	s_mov_b64 exec, s[22:23]
	v_mul_f32_e32 v21, 0x52800000, v95
	v_sub_u32_e32 v19, 0x1fff, v19
	v_ashrrev_i32_e32 v22, 31, v21
	v_lshl_add_u32 v20, v17, 2, v169
	v_bitop3_b32 v21, v22, v21, s64 bitop3:0x36
	v_and_or_b32 v21, v21, s65, v19
	ds_write_b32 v20, v21
	s_mov_b64 exec, -1
	v_cmp_ge_f32_e64 s[44:45], v97, v122
	v_cmp_ge_f32_e64 s[22:23], v97, v123
	s_andn2_b64 s[22:23], s[22:23], s[44:45]
	s_mov_b64 exec, s[44:45]
	ds_add_rtn_u32 v17, v180, v222
	s_mov_b64 exec, s[22:23]
	ds_add_rtn_u32 v17, v171, v222
	s_mov_b64 exec, -1
	v_or_b32_e32 v18, 16, v124
	s_waitcnt lgkmcnt(4)
;     ...
;         const unsigned s0 = (unsigned)(64 * kt + 32 * kb + 4 * hi);
; #pragma unroll
;         for (int r = 0; r < 16; ++r) { const unsigned s = s0 + (unsigned)((r & 3) + 8 * (r >> 2));
;             if (MODE == 5) { __hip_atomic_fetch_add(hist + 64 * bucketf(sc[r]), 1u, __ATOMIC_RELAXED, __HIP_MEMORY_SCOPE_WORKGROUP); continue; }
;             if (MODE == 6) {
;                 if (sc[r] >= t_hi) { const unsigned pos = __hip_atomic_fetch_add(cnt, 1u, __ATOMIC_RELAXED, __HIP_MEMORY_SCOPE_WORKGROUP); sel[pos & 255u] = (unsigned short)s; }
;                 else if (sc[r] >= t_lo) { const unsigned key = (sortable(sc[r]) & 0xFFFFE000u) | (8191u - s);
;                     const unsigned pos = __hip_atomic_fetch_add(ccnt, 1u, __ATOMIC_RELAXED, __HIP_MEMORY_SCOPE_WORKGROUP); cand[pos & (DS_CAP - 1)] = key; }
;                 continue; }
;             if (MODE == 7) { if (bucketf(sc[r]) == (int)pref) { const unsigned key = (sortable(sc[r]) & 0xFFFFE000u) | (8191u - s);
;                     __hip_atomic_fetch_add(hist + 64 * ((key >> 12) & 255u), 1u, __ATOMIC_RELAXED, __HIP_MEMORY_SCOPE_WORKGROUP); } continue; }
;             if (MODE == 8) { const int dA = bucketf(sc[r]);
;                 if (dA > (int)pref) { const unsigned pos = __hip_atomic_fetch_add(cnt, 1u, __ATOMIC_RELAXED, __HIP_MEMORY_SCOPE_WORKGROUP); sel[pos & 255u] = (unsigned short)s; }
;                 else if (dA == (int)pref) { const unsigned key = (sortable(sc[r]) & 0xFFFFE000u) | (8191u - s); const unsigned sub = (key >> 12) & 255u;
;                     if (sub > pref2) { const unsigned pos = __hip_atomic_fetch_add(cnt, 1u, __ATOMIC_RELAXED, __HIP_MEMORY_SCOPE_WORKGROUP); sel[pos & 255u] = (unsigned short)s; }
;                     else if (sub == pref2) { const unsigned pos = __hip_atomic_fetch_add(ccnt, 1u, __ATOMIC_RELAXED, __HIP_MEMORY_SCOPE_WORKGROUP); cand[pos & (DS_CAP - 1)] = key; } }
;                 continue; }
;             const unsigned key = (sortable(sc[r]) & 0xFFFFE000u) | (8191u - s);
;             if (MODE < 4) { bool ok = true; if (SHIFT < 24) ok = (key >> ((SHIFT + 8) & 31)) == pref;
;                 if (ok) __hip_atomic_fetch_add(hist + 64 * ((key >> (SHIFT & 31)) & 255u), 1u, __ATOMIC_RELAXED, __HIP_MEMORY_SCOPE_WORKGROUP); }
	v_and_b32_e32 v16, 0xff, v16
	s_mov_b64 exec, s[40:41]
	v_lshl_add_u32 v20, v16, 1, v179
	ds_write_b16 v20, v18
	s_mov_b64 exec, s[42:43]
	v_mul_f32_e32 v21, 0x52800000, v96
	v_sub_u32_e32 v18, 0x1fff, v18
	v_ashrrev_i32_e32 v22, 31, v21
	v_lshl_add_u32 v20, v16, 2, v169
	v_bitop3_b32 v21, v22, v21, s64 bitop3:0x36
	v_and_or_b32 v21, v21, s65, v18
	ds_write_b32 v20, v21
	s_mov_b64 exec, -1
	v_cmp_ge_f32_e64 s[40:41], v98, v122
	v_cmp_ge_f32_e64 s[42:43], v98, v123
	s_andn2_b64 s[42:43], s[42:43], s[40:41]
	s_mov_b64 exec, s[40:41]
	ds_add_rtn_u32 v16, v180, v222
	s_mov_b64 exec, s[42:43]
	ds_add_rtn_u32 v16, v171, v222
	s_mov_b64 exec, -1
	v_or_b32_e32 v19, 17, v124
	s_waitcnt lgkmcnt(4)
	v_and_b32_e32 v17, 0xff, v17
	s_mov_b64 exec, s[44:45]
	v_lshl_add_u32 v20, v17, 1, v179
	ds_write_b16 v20, v19
	s_mov_b64 exec, s[22:23]
	v_mul_f32_e32 v21, 0x52800000, v97
	v_sub_u32_e32 v19, 0x1fff, v19
	v_ashrrev_i32_e32 v22, 31, v21
	v_lshl_add_u32 v20, v17, 2, v169
	v_bitop3_b32 v21, v22, v21, s64 bitop3:0x36
	v_and_or_b32 v21, v21, s65, v19
	ds_write_b32 v20, v21
	s_mov_b64 exec, -1
	v_cmp_ge_f32_e64 s[44:45], v99, v122
	v_cmp_ge_f32_e64 s[22:23], v99, v123
	s_andn2_b64 s[22:23], s[22:23], s[44:45]
	s_mov_b64 exec, s[44:45]
	ds_add_rtn_u32 v17, v180, v222
	s_mov_b64 exec, s[22:23]
	ds_add_rtn_u32 v17, v171, v222
	s_mov_b64 exec, -1
	v_or_b32_e32 v18, 18, v124
	s_waitcnt lgkmcnt(4)
	v_and_b32_e32 v16, 0xff, v16
	s_mov_b64 exec, s[40:41]
	v_lshl_add_u32 v20, v16, 1, v179
	ds_write_b16 v20, v18
	s_mov_b64 exec, s[42:43]
	v_mul_f32_e32 v21, 0x52800000, v98
	v_sub_u32_e32 v18, 0x1fff, v18
	v_ashrrev_i32_e32 v22, 31, v21
	v_lshl_add_u32 v20, v16, 2, v169
	v_bitop3_b32 v21, v22, v21, s64 bitop3:0x36
	v_and_or_b32 v21, v21, s65, v18
	ds_write_b32 v20, v21
	s_mov_b64 exec, -1
	v_cmp_ge_f32_e64 s[40:41], v100, v122
	v_cmp_ge_f32_e64 s[42:43], v100, v123
	s_andn2_b64 s[42:43], s[42:43], s[40:41]
	s_mov_b64 exec, s[40:41]
	ds_add_rtn_u32 v16, v180, v222
	s_mov_b64 exec, s[42:43]
	ds_add_rtn_u32 v16, v171, v222
	s_mov_b64 exec, -1
	v_or_b32_e32 v19, 19, v124
	s_waitcnt lgkmcnt(4)
	v_and_b32_e32 v17, 0xff, v17
	s_mov_b64 exec, s[44:45]
	v_lshl_add_u32 v20, v17, 1, v179
	ds_write_b16 v20, v19
	s_mov_b64 exec, s[22:23]
	v_mul_f32_e32 v21, 0x52800000, v99
	v_sub_u32_e32 v19, 0x1fff, v19
	v_ashrrev_i32_e32 v22, 31, v21
	v_lshl_add_u32 v20, v17, 2, v169
	v_bitop3_b32 v21, v22, v21, s64 bitop3:0x36
	v_and_or_b32 v21, v21, s65, v19
	ds_write_b32 v20, v21
	s_mov_b64 exec, -1
	v_cmp_ge_f32_e64 s[44:45], v101, v122
	v_cmp_ge_f32_e64 s[22:23], v101, v123
	s_andn2_b64 s[22:23], s[22:23], s[44:45]
	s_mov_b64 exec, s[44:45]
	ds_add_rtn_u32 v17, v180, v222
	s_mov_b64 exec, s[22:23]
	ds_add_rtn_u32 v17, v171, v222
	s_mov_b64 exec, -1
	v_or_b32_e32 v18, 24, v124
	s_waitcnt lgkmcnt(4)
	v_and_b32_e32 v16, 0xff, v16
	s_mov_b64 exec, s[40:41]
	v_lshl_add_u32 v20, v16, 1, v179
	ds_write_b16 v20, v18
	s_mov_b64 exec, s[42:43]
	v_mul_f32_e32 v21, 0x52800000, v100
	v_sub_u32_e32 v18, 0x1fff, v18
	v_ashrrev_i32_e32 v22, 31, v21
	v_lshl_add_u32 v20, v16, 2, v169
	v_bitop3_b32 v21, v22, v21, s64 bitop3:0x36
	v_and_or_b32 v21, v21, s65, v18
	ds_write_b32 v20, v21
	s_mov_b64 exec, -1
	v_cmp_ge_f32_e64 s[40:41], v102, v122
	v_cmp_ge_f32_e64 s[42:43], v102, v123
	s_andn2_b64 s[42:43], s[42:43], s[40:41]
	s_mov_b64 exec, s[40:41]
	ds_add_rtn_u32 v16, v180, v222
	s_mov_b64 exec, s[42:43]
	ds_add_rtn_u32 v16, v171, v222
	s_mov_b64 exec, -1
	v_or_b32_e32 v19, 25, v124
	s_waitcnt lgkmcnt(4)
	v_and_b32_e32 v17, 0xff, v17
	s_mov_b64 exec, s[44:45]
	v_lshl_add_u32 v20, v17, 1, v179
	ds_write_b16 v20, v19
	s_mov_b64 exec, s[22:23]
	v_mul_f32_e32 v21, 0x52800000, v101
	v_sub_u32_e32 v19, 0x1fff, v19
	v_ashrrev_i32_e32 v22, 31, v21
	v_lshl_add_u32 v20, v17, 2, v169
	v_bitop3_b32 v21, v22, v21, s64 bitop3:0x36
	v_and_or_b32 v21, v21, s65, v19
	ds_write_b32 v20, v21
	s_mov_b64 exec, -1
	v_cmp_ge_f32_e64 s[44:45], v103, v122
	v_cmp_ge_f32_e64 s[22:23], v103, v123
	s_andn2_b64 s[22:23], s[22:23], s[44:45]
	s_mov_b64 exec, s[44:45]
	ds_add_rtn_u32 v17, v180, v222
	s_mov_b64 exec, s[22:23]
	ds_add_rtn_u32 v17, v171, v222
	s_mov_b64 exec, -1
	v_or_b32_e32 v18, 26, v124
	s_waitcnt lgkmcnt(4)
	v_and_b32_e32 v16, 0xff, v16
	s_mov_b64 exec, s[40:41]
	v_lshl_add_u32 v20, v16, 1, v179
	ds_write_b16 v20, v18
	s_mov_b64 exec, s[42:43]
	v_mul_f32_e32 v21, 0x52800000, v102
	v_sub_u32_e32 v18, 0x1fff, v18
	v_ashrrev_i32_e32 v22, 31, v21
	v_lshl_add_u32 v20, v16, 2, v169
	v_bitop3_b32 v21, v22, v21, s64 bitop3:0x36
	v_and_or_b32 v21, v21, s65, v18
	ds_write_b32 v20, v21
	s_mov_b64 exec, -1
	v_or_b32_e32 v19, 27, v124
	s_waitcnt lgkmcnt(2)
	v_and_b32_e32 v17, 0xff, v17
	s_mov_b64 exec, s[44:45]
	v_lshl_add_u32 v20, v17, 1, v179
	ds_write_b16 v20, v19
	s_mov_b64 exec, s[22:23]
	v_mul_f32_e32 v21, 0x52800000, v103
	v_sub_u32_e32 v19, 0x1fff, v19
	v_ashrrev_i32_e32 v22, 31, v21
	v_lshl_add_u32 v20, v17, 2, v169
	v_bitop3_b32 v21, v22, v21, s64 bitop3:0x36
	v_and_or_b32 v21, v21, s65, v19
	ds_write_b32 v20, v21
	s_mov_b64 exec, -1
	s_waitcnt vmcnt(0)
	v_mov_b64_e32 v[132:133], v[64:65]
	v_mov_b64_e32 v[134:135], v[66:67]
	v_mov_b64_e32 v[128:129], v[68:69]
	v_mov_b64_e32 v[130:131], v[70:71]
	s_cmp_lg_u32 s25, s1
	s_mov_b32 s18, s1
	s_cbranch_scc1 .Lm6_loop
